# code placement: one s_nop 0 at kernel entry shifts the whole instruction stream by 4 bytes (five of the seven GEMM K-loop heads, G5 and G6 among them, now start on an 8-byte boundary)
# baseline (speedup 1.0000x reference)
_Z9trunk_fwd4Args:
	s_nop 0
	s_load_dword s3, s[0:1], 0xf0
	s_add_u32 s4, s0, 0xf0
	s_addc_u32 s5, s1, 0
	v_readfirstlane_b32 s12, v0
	v_writelane_b32 v246, s4, 0
	s_mov_b32 s13, s2
	s_nop 0
	v_writelane_b32 v246, s5, 1
	s_waitcnt lgkmcnt(0)
	v_writelane_b32 v246, s3, 2
	s_and_b32 s3, s3, 7
	s_cmp_eq_u32 s3, 0
	s_cselect_b64 s[34:35], -1, 0
	s_cmp_lg_u32 s3, 0
	s_cselect_b64 s[4:5], -1, 0
	s_and_b64 vcc, exec, s[4:5]
	s_cbranch_vccnz .LBB0_2
	s_load_dword s3, s[0:1], 0xf0
	s_ashr_i32 s6, s2, 31
	s_lshr_b32 s6, s6, 29
	s_add_i32 s6, s2, s6
	s_ashr_i32 s7, s6, 3
	s_and_b32 s6, s6, -8
	s_waitcnt lgkmcnt(0)
	s_ashr_i32 s3, s3, 3
	s_sub_i32 s6, s2, s6
	s_mul_i32 s3, s3, s6
	s_add_i32 s13, s3, s7
